# grid barrier: the last XCD leader no longer posts the unused TOPGEN word (leaders poll the arrival counter)
# baseline (speedup 1.0000x reference)
.LBB0_261:
	s_or_b64 exec, exec, s[8:9]
	v_cvt_f32_u32_e32 v3, v0
	s_waitcnt vmcnt(0)
	v_readfirstlane_b32 s6, v2
	s_add_u32 s8, s82, 0x983500
	s_addc_u32 s9, s83, 0
	v_rcp_iflag_f32_e32 v3, v3
	v_add_u32_e32 v1, s6, v1
	v_add_u32_e32 v4, 1, v1
	s_mov_b64 s[10:11], 0
	v_mul_f32_e32 v2, 0x4f7ffffe, v3
	v_cvt_u32_f32_e32 v2, v2
	v_sub_u32_e32 v3, 0, v0
	v_mul_lo_u32 v3, v3, v2
	v_mul_hi_u32 v3, v2, v3
	v_add_u32_e32 v2, v2, v3
	v_mul_hi_u32 v2, v1, v2
	v_mul_lo_u32 v3, v2, v0
	v_sub_u32_e32 v1, v1, v3
	v_add_u32_e32 v5, 1, v2
	v_cmp_ge_u32_e32 vcc, v1, v0
	v_sub_u32_e32 v3, v1, v0
	s_nop 0
	v_cndmask_b32_e32 v2, v2, v5, vcc
	v_cndmask_b32_e32 v1, v1, v3, vcc
	v_add_u32_e32 v3, 1, v2
	v_cmp_ge_u32_e32 vcc, v1, v0
	s_nop 1
	v_cndmask_b32_e32 v2, v2, v3, vcc
	v_mul_lo_u32 v1, v0, v2
	v_add_u32_e32 v0, v1, v0
	v_cmp_ne_u32_e32 vcc, v4, v0
	v_mov_b32_e32 v5, v0
	v_mov_b64_e32 v[0:1], s[8:9]
	s_and_saveexec_b64 s[6:7], vcc
	s_cbranch_execz .LBB0_273
	v_mov_b32_e32 v0, 0
	global_load_dword v1, v0, s[8:9] offset:-256 sc1
	s_mov_b64 s[18:19], 0
	s_waitcnt vmcnt(0)
	v_cmp_lt_u32_e32 vcc, v1, v5
	s_and_saveexec_b64 s[16:17], vcc
	s_cbranch_execz .LBB0_272
	s_add_u32 s10, s82, 0x980200
	s_addc_u32 s11, s83, 0
	s_mov_b32 s28, 1
	s_branch .LBB0_265

.LBB0_483:
	s_or_b64 exec, exec, s[8:9]
	v_cvt_f32_u32_e32 v3, v0
	s_waitcnt vmcnt(0)
	v_readfirstlane_b32 s6, v2
	s_add_u32 s8, s82, 0x983500
	s_addc_u32 s9, s83, 0
	v_rcp_iflag_f32_e32 v3, v3
	v_add_u32_e32 v1, s6, v1
	v_add_u32_e32 v4, 1, v1
	s_mov_b64 s[10:11], 0
	v_mul_f32_e32 v2, 0x4f7ffffe, v3
	v_cvt_u32_f32_e32 v2, v2
	v_sub_u32_e32 v3, 0, v0
	v_mul_lo_u32 v3, v3, v2
	v_mul_hi_u32 v3, v2, v3
	v_add_u32_e32 v2, v2, v3
	v_mul_hi_u32 v2, v1, v2
	v_mul_lo_u32 v3, v2, v0
	v_sub_u32_e32 v1, v1, v3
	v_add_u32_e32 v5, 1, v2
	v_cmp_ge_u32_e32 vcc, v1, v0
	v_sub_u32_e32 v3, v1, v0
	s_nop 0
	v_cndmask_b32_e32 v2, v2, v5, vcc
	v_cndmask_b32_e32 v1, v1, v3, vcc
	v_add_u32_e32 v3, 1, v2
	v_cmp_ge_u32_e32 vcc, v1, v0
	s_nop 1
	v_cndmask_b32_e32 v2, v2, v3, vcc
	v_mul_lo_u32 v1, v0, v2
	v_add_u32_e32 v0, v1, v0
	v_cmp_ne_u32_e32 vcc, v4, v0
	v_mov_b32_e32 v5, v0
	v_mov_b64_e32 v[0:1], s[8:9]
	s_and_saveexec_b64 s[6:7], vcc
	s_cbranch_execz .LBB0_495
	v_mov_b32_e32 v0, 0
	global_load_dword v1, v0, s[8:9] offset:-256 sc1
	s_mov_b64 s[20:21], 0
	s_waitcnt vmcnt(0)
	v_cmp_lt_u32_e32 vcc, v1, v5
	s_and_saveexec_b64 s[18:19], vcc
	s_cbranch_execz .LBB0_494
	s_add_u32 s10, s82, 0x980200
	s_addc_u32 s11, s83, 0
	s_mov_b32 s30, 1
	s_branch .LBB0_487

.LBB0_650:
	s_or_b64 exec, exec, s[8:9]
	v_cvt_f32_u32_e32 v3, v0
	s_waitcnt vmcnt(0)
	v_readfirstlane_b32 s6, v2
	s_add_u32 s8, s82, 0x983500
	s_addc_u32 s9, s83, 0
	v_rcp_iflag_f32_e32 v3, v3
	v_add_u32_e32 v1, s6, v1
	v_add_u32_e32 v4, 1, v1
	s_mov_b64 s[10:11], 0
	v_mul_f32_e32 v2, 0x4f7ffffe, v3
	v_cvt_u32_f32_e32 v2, v2
	v_sub_u32_e32 v3, 0, v0
	v_mul_lo_u32 v3, v3, v2
	v_mul_hi_u32 v3, v2, v3
	v_add_u32_e32 v2, v2, v3
	v_mul_hi_u32 v2, v1, v2
	v_mul_lo_u32 v3, v2, v0
	v_sub_u32_e32 v1, v1, v3
	v_add_u32_e32 v5, 1, v2
	v_cmp_ge_u32_e32 vcc, v1, v0
	v_sub_u32_e32 v3, v1, v0
	s_nop 0
	v_cndmask_b32_e32 v2, v2, v5, vcc
	v_cndmask_b32_e32 v1, v1, v3, vcc
	v_add_u32_e32 v3, 1, v2
	v_cmp_ge_u32_e32 vcc, v1, v0
	s_nop 1
	v_cndmask_b32_e32 v2, v2, v3, vcc
	v_mul_lo_u32 v1, v0, v2
	v_add_u32_e32 v0, v1, v0
	v_cmp_ne_u32_e32 vcc, v4, v0
	v_mov_b32_e32 v5, v0
	v_mov_b64_e32 v[0:1], s[8:9]
	s_and_saveexec_b64 s[6:7], vcc
	s_cbranch_execz .LBB0_662
	v_mov_b32_e32 v0, 0
	global_load_dword v1, v0, s[8:9] offset:-256 sc1
	s_mov_b64 s[14:15], 0
	s_waitcnt vmcnt(0)
	v_cmp_lt_u32_e32 vcc, v1, v5
	s_and_saveexec_b64 s[12:13], vcc
	s_cbranch_execz .LBB0_661
	s_add_u32 s10, s82, 0x980200
	s_addc_u32 s11, s83, 0
	s_mov_b32 s24, 1
	s_branch .LBB0_654

.LBB0_831:
	s_or_b64 exec, exec, s[6:7]
	v_cvt_f32_u32_e32 v3, v0
	s_waitcnt vmcnt(0)
	v_readfirstlane_b32 s4, v2
	s_add_u32 s6, s70, 0x983500
	s_addc_u32 s7, s71, 0
	v_rcp_iflag_f32_e32 v3, v3
	v_add_u32_e32 v1, s4, v1
	v_add_u32_e32 v4, 1, v1
	s_mov_b64 s[8:9], 0
	v_mul_f32_e32 v2, 0x4f7ffffe, v3
	v_cvt_u32_f32_e32 v2, v2
	v_sub_u32_e32 v3, 0, v0
	v_mul_lo_u32 v3, v3, v2
	v_mul_hi_u32 v3, v2, v3
	v_add_u32_e32 v2, v2, v3
	v_mul_hi_u32 v2, v1, v2
	v_mul_lo_u32 v3, v2, v0
	v_sub_u32_e32 v1, v1, v3
	v_add_u32_e32 v5, 1, v2
	v_cmp_ge_u32_e32 vcc, v1, v0
	v_sub_u32_e32 v3, v1, v0
	s_nop 0
	v_cndmask_b32_e32 v2, v2, v5, vcc
	v_cndmask_b32_e32 v1, v1, v3, vcc
	v_add_u32_e32 v3, 1, v2
	v_cmp_ge_u32_e32 vcc, v1, v0
	s_nop 1
	v_cndmask_b32_e32 v2, v2, v3, vcc
	v_mul_lo_u32 v1, v0, v2
	v_add_u32_e32 v0, v1, v0
	v_cmp_ne_u32_e32 vcc, v4, v0
	v_mov_b32_e32 v5, v0
	v_mov_b64_e32 v[0:1], s[6:7]
	s_and_saveexec_b64 s[4:5], vcc
	s_cbranch_execz .LBB0_843
	v_mov_b32_e32 v0, 0
	global_load_dword v1, v0, s[6:7] offset:-256 sc1
	s_mov_b64 s[12:13], 0
	s_waitcnt vmcnt(0)
	v_cmp_lt_u32_e32 vcc, v1, v5
	s_and_saveexec_b64 s[10:11], vcc
	s_cbranch_execz .LBB0_842
	s_add_u32 s8, s70, 0x980200
	s_addc_u32 s9, s71, 0
	s_mov_b32 s22, 1
	s_branch .LBB0_835

.LBB0_971:
	s_or_b64 exec, exec, s[10:11]
	v_cvt_f32_u32_e32 v3, v0
	s_waitcnt vmcnt(0)
	v_readfirstlane_b32 s8, v2
	s_add_u32 s10, s70, 0x983500
	s_addc_u32 s11, s71, 0
	v_rcp_iflag_f32_e32 v3, v3
	v_add_u32_e32 v1, s8, v1
	v_add_u32_e32 v4, 1, v1
	s_mov_b64 s[12:13], 0
	v_mul_f32_e32 v2, 0x4f7ffffe, v3
	v_cvt_u32_f32_e32 v2, v2
	v_sub_u32_e32 v3, 0, v0
	v_mul_lo_u32 v3, v3, v2
	v_mul_hi_u32 v3, v2, v3
	v_add_u32_e32 v2, v2, v3
	v_mul_hi_u32 v2, v1, v2
	v_mul_lo_u32 v3, v2, v0
	v_sub_u32_e32 v1, v1, v3
	v_add_u32_e32 v5, 1, v2
	v_cmp_ge_u32_e32 vcc, v1, v0
	v_sub_u32_e32 v3, v1, v0
	s_nop 0
	v_cndmask_b32_e32 v2, v2, v5, vcc
	v_cndmask_b32_e32 v1, v1, v3, vcc
	v_add_u32_e32 v3, 1, v2
	v_cmp_ge_u32_e32 vcc, v1, v0
	s_nop 1
	v_cndmask_b32_e32 v2, v2, v3, vcc
	v_mul_lo_u32 v1, v0, v2
	v_add_u32_e32 v0, v1, v0
	v_cmp_ne_u32_e32 vcc, v4, v0
	v_mov_b32_e32 v5, v0
	v_mov_b64_e32 v[0:1], s[10:11]
	s_and_saveexec_b64 s[8:9], vcc
	s_cbranch_execz .LBB0_983
	v_mov_b32_e32 v0, 0
	global_load_dword v1, v0, s[10:11] offset:-256 sc1
	s_mov_b64 s[16:17], 0
	s_waitcnt vmcnt(0)
	v_cmp_lt_u32_e32 vcc, v1, v5
	s_and_saveexec_b64 s[14:15], vcc
	s_cbranch_execz .LBB0_982
	s_add_u32 s12, s70, 0x980200
	s_addc_u32 s13, s71, 0
	s_mov_b32 s26, 1
	s_branch .LBB0_975

.LBB0_1076:
	s_or_b64 exec, exec, s[8:9]
	v_cvt_f32_u32_e32 v3, v0
	s_waitcnt vmcnt(0)
	v_readfirstlane_b32 s6, v2
	s_add_u32 s8, s70, 0x983500
	s_addc_u32 s9, s71, 0
	v_rcp_iflag_f32_e32 v3, v3
	v_add_u32_e32 v1, s6, v1
	v_add_u32_e32 v4, 1, v1
	s_mov_b64 s[10:11], 0
	v_mul_f32_e32 v2, 0x4f7ffffe, v3
	v_cvt_u32_f32_e32 v2, v2
	v_sub_u32_e32 v3, 0, v0
	v_mul_lo_u32 v3, v3, v2
	v_mul_hi_u32 v3, v2, v3
	v_add_u32_e32 v2, v2, v3
	v_mul_hi_u32 v2, v1, v2
	v_mul_lo_u32 v3, v2, v0
	v_sub_u32_e32 v1, v1, v3
	v_add_u32_e32 v5, 1, v2
	v_cmp_ge_u32_e32 vcc, v1, v0
	v_sub_u32_e32 v3, v1, v0
	s_nop 0
	v_cndmask_b32_e32 v2, v2, v5, vcc
	v_cndmask_b32_e32 v1, v1, v3, vcc
	v_add_u32_e32 v3, 1, v2
	v_cmp_ge_u32_e32 vcc, v1, v0
	s_nop 1
	v_cndmask_b32_e32 v2, v2, v3, vcc
	v_mul_lo_u32 v1, v0, v2
	v_add_u32_e32 v0, v1, v0
	v_cmp_ne_u32_e32 vcc, v4, v0
	v_mov_b32_e32 v5, v0
	v_mov_b64_e32 v[0:1], s[8:9]
	s_and_saveexec_b64 s[6:7], vcc
	s_cbranch_execz .LBB0_1088
	v_mov_b32_e32 v0, 0
	global_load_dword v1, v0, s[8:9] offset:-256 sc1
	s_mov_b64 s[14:15], 0
	s_waitcnt vmcnt(0)
	v_cmp_lt_u32_e32 vcc, v1, v5
	s_and_saveexec_b64 s[12:13], vcc
	s_cbranch_execz .LBB0_1087
	s_add_u32 s10, s70, 0x980200
	s_addc_u32 s11, s71, 0
	s_mov_b32 s24, 1
	s_branch .LBB0_1080
